# stack4 + GEMM1 K-loop: static s_setprio 1 for waves 0-3 instead (A/B of the half), per-segment flips deleted
# speedup vs baseline: 1.0051x; 1.0051x over previous
.LBB0_398:
	v_readfirstlane_b32 s98, v212
	s_nop 3
	s_lshr_b32 s98, s98, 6
	s_cmp_lt_u32 s98, 4
	s_cbranch_scc0 .Lprio_done
	s_setprio 1
